# attention unit epilogue: two-map combine split across all 8 waves (map-0 waves combine per-lane rows 0-7, map-1 waves rows 8-15), halving the post-barrier critical path
# speedup vs baseline: 1.0039x; 1.0039x over previous
; #define LAS __attribute__((address_space(3)))
; __device__ __forceinline__ int crow(int r, int hi) { return (r & 3) + 8 * (r >> 2) + 4 * hi; }
; __device__ __forceinline__ void attn_unit(LAS unsigned char* lds, bf16_t* Zg, const unsigned char* KVg, int S, int b, int h, int qb, const float* lq1, const float* lk1, const float* lq2, const float* lk2, const float* subln_g, const float* rel_bias, bool dostore = true) {
;     ...
;     for (int g = 0; g < 4; ++g) { const f32x4 a4 = *(const LAS f32x4*)(wsf + 8 * g + 4 * hi); inv[4 * g] = a4.x; inv[4 * g + 1] = a4.y; inv[4 * g + 2] = a4.z; inv[4 * g + 3] = a4.w; }
;     LAS float* exch = (LAS float*)lds;
;     if (mp == 1) {
; #pragma unroll
;         for (int db = 0; db < 4; ++db)
; #pragma unroll
;             for (int r = 0; r < 16; ++r) exch[(32 * qsub + crow(r, hi)) * 128 + db * 32 + r32] = o[db][r] * inv[r];
;     }
;     __syncthreads();
;     if (mp == 0) {
;         float ss[16];
; #pragma unroll
;         for (int r = 0; r < 16; ++r) { float a = 0.f;
; #pragma unroll
;             for (int db = 0; db < 4; ++db) { const float d = o[db][r] * inv[r] - exch[(32 * qsub + crow(r, hi)) * 128 + db * 32 + r32]; o[db][r] = d; a += d * d; }
;             ss[r] = a; }
.LBB0_285:
	s_or_b64 exec, exec, s[6:7]
	s_waitcnt lgkmcnt(0)
	ds_read_b128 v[78:81], v212
	ds_read_b128 v[74:77], v212 offset:32
	s_waitcnt lgkmcnt(2)
	ds_read_b128 v[70:73], v212 offset:64
	ds_read_b128 v[66:69], v212 offset:96
	s_cmp_lg_u32 s89, 1
	v_lshlrev_b32_e32 v82, 2, v210
	s_cbranch_scc1 .Lcmb_map0
	v_or_b32_e32 v0, s85, v211
	v_lshlrev_b32_e32 v0, 9, v0
	v_add3_u32 v0, 0, v82, v0
	global_load_dword v190, v82, s[68:69]
	global_load_dword v191, v82, s[68:69] offset:128
	global_load_dword v192, v82, s[68:69] offset:256
	global_load_dword v193, v82, s[68:69] offset:384
	v_add_u32_e32 v105, 0x400, v0
	v_add_u32_e32 v106, 0x1000, v0
	v_add_u32_e32 v107, 0x1400, v0
	v_add_u32_e32 v108, 0x2000, v0
	v_add_u32_e32 v109, 0x2400, v0
	v_add_u32_e32 v110, 0x3000, v0
	v_add_u32_e32 v111, 0x3400, v0
	s_waitcnt lgkmcnt(0)
	v_mul_f32_e32 v89, v50, v78
	v_mul_f32_e32 v90, v34, v78
	ds_write2_b32 v0, v89, v90 offset1:32
	v_mul_f32_e32 v91, v18, v78
	v_mul_f32_e32 v92, v2, v78
	ds_write2_b32 v0, v91, v92 offset0:64 offset1:96
	v_mul_f32_e32 v93, v51, v79
	v_mul_f32_e32 v94, v35, v79
	ds_write2_b32 v0, v93, v94 offset0:128 offset1:160
	v_mul_f32_e32 v95, v19, v79
	v_mul_f32_e32 v96, v3, v79
	ds_write2_b32 v0, v95, v96 offset0:192 offset1:224
	v_mul_f32_e32 v97, v52, v80
	v_mul_f32_e32 v98, v36, v80
	ds_write2_b32 v105, v97, v98 offset1:32
	v_mul_f32_e32 v99, v20, v80
	v_mul_f32_e32 v100, v4, v80
	ds_write2_b32 v105, v99, v100 offset0:64 offset1:96
	v_mul_f32_e32 v101, v53, v81
	v_mul_f32_e32 v102, v37, v81
	ds_write2_b32 v105, v101, v102 offset0:128 offset1:160
	v_mul_f32_e32 v103, v21, v81
	v_mul_f32_e32 v104, v5, v81
	ds_write2_b32 v105, v103, v104 offset0:192 offset1:224
	v_mul_f32_e32 v89, v54, v74
	v_mul_f32_e32 v90, v38, v74
	ds_write2_b32 v106, v89, v90 offset1:32
	v_mul_f32_e32 v91, v22, v74
	v_mul_f32_e32 v92, v6, v74
	ds_write2_b32 v106, v91, v92 offset0:64 offset1:96
	v_mul_f32_e32 v93, v55, v75
	v_mul_f32_e32 v94, v39, v75
	ds_write2_b32 v106, v93, v94 offset0:128 offset1:160
	v_mul_f32_e32 v95, v23, v75
	v_mul_f32_e32 v96, v7, v75
	ds_write2_b32 v106, v95, v96 offset0:192 offset1:224
	v_mul_f32_e32 v97, v56, v76
	v_mul_f32_e32 v98, v40, v76
	ds_write2_b32 v107, v97, v98 offset1:32
	v_mul_f32_e32 v99, v24, v76
	v_mul_f32_e32 v100, v8, v76
	ds_write2_b32 v107, v99, v100 offset0:64 offset1:96
	v_mul_f32_e32 v101, v57, v77
	v_mul_f32_e32 v102, v41, v77
	ds_write2_b32 v107, v101, v102 offset0:128 offset1:160
	v_mul_f32_e32 v103, v25, v77
	v_mul_f32_e32 v104, v9, v77
	ds_write2_b32 v107, v103, v104 offset0:192 offset1:224
	s_waitcnt lgkmcnt(0)
	s_barrier
	ds_read2_b32 v[178:179], v108 offset1:32
	ds_read2_b32 v[180:181], v108 offset0:64 offset1:96
	ds_read2_b32 v[182:183], v108 offset0:128 offset1:160
	ds_read2_b32 v[184:185], v108 offset0:192 offset1:224
	ds_read2_b32 v[186:187], v109 offset1:32
	ds_read2_b32 v[188:189], v109 offset0:64 offset1:96
	s_waitcnt lgkmcnt(5)
	v_fma_f32 v58, -v58, v70, v178
	v_fma_f32 v42, -v42, v70, v179
	ds_read2_b32 v[178:179], v109 offset0:128 offset1:160
	s_waitcnt lgkmcnt(5)
	v_fma_f32 v26, -v26, v70, v180
	v_fma_f32 v10, -v10, v70, v181
	ds_read2_b32 v[180:181], v109 offset0:192 offset1:224
	v_mul_f32_e32 v89, v42, v42
	v_fmac_f32_e32 v89, v58, v58
	v_fmac_f32_e32 v89, v26, v26
	v_fmac_f32_e32 v89, v10, v10
	s_waitcnt lgkmcnt(5)
	v_fma_f32 v59, -v59, v71, v182
	v_fma_f32 v43, -v43, v71, v183
	ds_read2_b32 v[182:183], v110 offset1:32
	s_waitcnt lgkmcnt(5)
	v_fma_f32 v27, -v27, v71, v184
	v_fma_f32 v11, -v11, v71, v185
	ds_read2_b32 v[184:185], v110 offset0:64 offset1:96
	v_mul_f32_e32 v90, v43, v43
	v_fmac_f32_e32 v90, v59, v59
	v_fmac_f32_e32 v90, v27, v27
	v_fmac_f32_e32 v90, v11, v11
	s_waitcnt lgkmcnt(5)
	v_fma_f32 v60, -v60, v72, v186
	v_fma_f32 v44, -v44, v72, v187
	ds_read2_b32 v[186:187], v110 offset0:128 offset1:160
	s_waitcnt lgkmcnt(5)
	v_fma_f32 v28, -v28, v72, v188
	v_fma_f32 v12, -v12, v72, v189
	ds_read2_b32 v[188:189], v110 offset0:192 offset1:224
	v_mul_f32_e32 v91, v44, v44
	v_fmac_f32_e32 v91, v60, v60
	v_fmac_f32_e32 v91, v28, v28
	v_fmac_f32_e32 v91, v12, v12
	s_waitcnt lgkmcnt(5)
	v_fma_f32 v61, -v61, v73, v178
	v_fma_f32 v45, -v45, v73, v179
	ds_read2_b32 v[178:179], v111 offset1:32
	s_waitcnt lgkmcnt(5)
	v_fma_f32 v29, -v29, v73, v180
	v_fma_f32 v13, -v13, v73, v181
	ds_read2_b32 v[180:181], v111 offset0:64 offset1:96
	v_mul_f32_e32 v92, v45, v45
	v_fmac_f32_e32 v92, v61, v61
	v_fmac_f32_e32 v92, v29, v29
	v_fmac_f32_e32 v92, v13, v13
	s_waitcnt lgkmcnt(5)
	v_fma_f32 v62, -v62, v66, v182
	v_fma_f32 v46, -v46, v66, v183
	ds_read2_b32 v[182:183], v111 offset0:128 offset1:160
	s_waitcnt lgkmcnt(5)
	v_fma_f32 v30, -v30, v66, v184
	v_fma_f32 v14, -v14, v66, v185
	ds_read2_b32 v[184:185], v111 offset0:192 offset1:224
	v_mul_f32_e32 v93, v46, v46
	v_fmac_f32_e32 v93, v62, v62
	v_fmac_f32_e32 v93, v30, v30
	v_fmac_f32_e32 v93, v14, v14
	s_waitcnt lgkmcnt(5)
	v_fma_f32 v63, -v63, v67, v186
	v_fma_f32 v47, -v47, v67, v187
	s_waitcnt lgkmcnt(4)
	v_fma_f32 v31, -v31, v67, v188
	v_fma_f32 v15, -v15, v67, v189
	v_mul_f32_e32 v94, v47, v47
	v_fmac_f32_e32 v94, v63, v63
	v_fmac_f32_e32 v94, v31, v31
	v_fmac_f32_e32 v94, v15, v15
	s_waitcnt lgkmcnt(3)
	v_fma_f32 v64, -v64, v68, v178
	v_fma_f32 v48, -v48, v68, v179
	s_waitcnt lgkmcnt(2)
	v_fma_f32 v32, -v32, v68, v180
	v_fma_f32 v16, -v16, v68, v181
	v_mul_f32_e32 v95, v48, v48
	v_fmac_f32_e32 v95, v64, v64
	v_fmac_f32_e32 v95, v32, v32
	v_fmac_f32_e32 v95, v16, v16
	s_waitcnt lgkmcnt(1)
	v_fma_f32 v65, -v65, v69, v182
	v_fma_f32 v49, -v49, v69, v183
	s_waitcnt lgkmcnt(0)
; __device__ __forceinline__ float shx(float v, int o, int lane) { return __int_as_float(__builtin_amdgcn_ds_bpermute((lane ^ o) << 2, __float_as_int(v))); }
; __device__ __forceinline__ void attn_unit(LAS unsigned char* lds, bf16_t* Zg, const unsigned char* KVg, int S, int b, int h, int qb, const float* lq1, const float* lk1, const float* lq2, const float* lk2, const float* subln_g, const float* rel_bias, bool dostore = true) {
;     ...
;         for (int r = 0; r < 16; ++r) {
; #pragma unroll
;             for (int sft = 1; sft < 32; sft <<= 1) ss[r] += shx(ss[r], sft, lane);
;             ss[r] = (1.0f - LAMBDA_INIT) / sqrtf(ss[r] * (1.0f / 128.0f) + EPS); }
	v_fma_f32 v33, -v33, v69, v184
	v_fma_f32 v17, -v17, v69, v185
	v_mul_f32_e32 v96, v49, v49
	v_fmac_f32_e32 v96, v65, v65
	v_fmac_f32_e32 v96, v33, v33
	v_fmac_f32_e32 v96, v17, v17
	s_nop 1
	v_mov_b32_dpp v84, v89 quad_perm:[1,0,3,2] row_mask:0xf bank_mask:0xf
	v_mov_b32_dpp v85, v90 quad_perm:[1,0,3,2] row_mask:0xf bank_mask:0xf
	v_mov_b32_dpp v86, v91 quad_perm:[1,0,3,2] row_mask:0xf bank_mask:0xf
	v_mov_b32_dpp v87, v92 quad_perm:[1,0,3,2] row_mask:0xf bank_mask:0xf
	v_add_f32_e32 v89, v89, v84
	v_add_f32_e32 v90, v90, v85
	v_add_f32_e32 v91, v91, v86
	v_add_f32_e32 v92, v92, v87
	v_mov_b32_dpp v84, v89 quad_perm:[2,3,0,1] row_mask:0xf bank_mask:0xf
	v_mov_b32_dpp v85, v90 quad_perm:[2,3,0,1] row_mask:0xf bank_mask:0xf
	v_mov_b32_dpp v86, v91 quad_perm:[2,3,0,1] row_mask:0xf bank_mask:0xf
	v_mov_b32_dpp v87, v92 quad_perm:[2,3,0,1] row_mask:0xf bank_mask:0xf
	v_add_f32_e32 v89, v89, v84
	v_add_f32_e32 v90, v90, v85
	v_add_f32_e32 v91, v91, v86
	v_add_f32_e32 v92, v92, v87
	v_mov_b32_dpp v84, v89 row_half_mirror row_mask:0xf bank_mask:0xf
	v_mov_b32_dpp v85, v90 row_half_mirror row_mask:0xf bank_mask:0xf
	v_mov_b32_dpp v86, v91 row_half_mirror row_mask:0xf bank_mask:0xf
	v_mov_b32_dpp v87, v92 row_half_mirror row_mask:0xf bank_mask:0xf
	v_add_f32_e32 v89, v89, v84
	v_add_f32_e32 v90, v90, v85
	v_add_f32_e32 v91, v91, v86
	v_add_f32_e32 v92, v92, v87
	v_mov_b32_dpp v84, v89 row_ror:8 row_mask:0xf bank_mask:0xf
	v_mov_b32_dpp v85, v90 row_ror:8 row_mask:0xf bank_mask:0xf
	v_mov_b32_dpp v86, v91 row_ror:8 row_mask:0xf bank_mask:0xf
	v_mov_b32_dpp v87, v92 row_ror:8 row_mask:0xf bank_mask:0xf
	v_add_f32_e32 v89, v89, v84
	v_add_f32_e32 v90, v90, v85
	v_add_f32_e32 v91, v91, v86
	v_add_f32_e32 v92, v92, v87
	v_mov_b32_e32 v84, v89
	v_mov_b32_e32 v85, v90
	v_mov_b32_e32 v86, v91
	v_mov_b32_e32 v87, v92
	v_permlane16_swap_b32_e32 v84, v89
	v_permlane16_swap_b32_e32 v85, v90
	v_permlane16_swap_b32_e32 v86, v91
	v_permlane16_swap_b32_e32 v87, v92
	v_add_f32_e32 v89, v89, v84
	v_add_f32_e32 v90, v90, v85
	v_add_f32_e32 v91, v91, v86
	v_add_f32_e32 v92, v92, v87
	s_nop 1
	v_mov_b32_dpp v84, v93 quad_perm:[1,0,3,2] row_mask:0xf bank_mask:0xf
	v_mov_b32_dpp v85, v94 quad_perm:[1,0,3,2] row_mask:0xf bank_mask:0xf
	v_mov_b32_dpp v86, v95 quad_perm:[1,0,3,2] row_mask:0xf bank_mask:0xf
	v_mov_b32_dpp v87, v96 quad_perm:[1,0,3,2] row_mask:0xf bank_mask:0xf
	v_add_f32_e32 v93, v93, v84
	v_add_f32_e32 v94, v94, v85
	v_add_f32_e32 v95, v95, v86
	v_add_f32_e32 v96, v96, v87
	v_mov_b32_dpp v84, v93 quad_perm:[2,3,0,1] row_mask:0xf bank_mask:0xf
	v_mov_b32_dpp v85, v94 quad_perm:[2,3,0,1] row_mask:0xf bank_mask:0xf
	v_mov_b32_dpp v86, v95 quad_perm:[2,3,0,1] row_mask:0xf bank_mask:0xf
	v_mov_b32_dpp v87, v96 quad_perm:[2,3,0,1] row_mask:0xf bank_mask:0xf
	v_add_f32_e32 v93, v93, v84
	v_add_f32_e32 v94, v94, v85
	v_add_f32_e32 v95, v95, v86
	v_add_f32_e32 v96, v96, v87
	v_mov_b32_dpp v84, v93 row_half_mirror row_mask:0xf bank_mask:0xf
	v_mov_b32_dpp v85, v94 row_half_mirror row_mask:0xf bank_mask:0xf
	v_mov_b32_dpp v86, v95 row_half_mirror row_mask:0xf bank_mask:0xf
	v_mov_b32_dpp v87, v96 row_half_mirror row_mask:0xf bank_mask:0xf
	v_add_f32_e32 v93, v93, v84
	v_add_f32_e32 v94, v94, v85
	v_add_f32_e32 v95, v95, v86
	v_add_f32_e32 v96, v96, v87
	v_mov_b32_dpp v84, v93 row_ror:8 row_mask:0xf bank_mask:0xf
	v_mov_b32_dpp v85, v94 row_ror:8 row_mask:0xf bank_mask:0xf
	v_mov_b32_dpp v86, v95 row_ror:8 row_mask:0xf bank_mask:0xf
	v_mov_b32_dpp v87, v96 row_ror:8 row_mask:0xf bank_mask:0xf
	v_add_f32_e32 v93, v93, v84
	v_add_f32_e32 v94, v94, v85
	v_add_f32_e32 v95, v95, v86
	v_add_f32_e32 v96, v96, v87
	v_mov_b32_e32 v84, v93
	v_mov_b32_e32 v85, v94
	v_mov_b32_e32 v86, v95
	v_mov_b32_e32 v87, v96
	v_permlane16_swap_b32_e32 v84, v93
	v_permlane16_swap_b32_e32 v85, v94
	v_permlane16_swap_b32_e32 v86, v95
	v_permlane16_swap_b32_e32 v87, v96
	v_add_f32_e32 v93, v93, v84
	v_add_f32_e32 v94, v94, v85
	v_add_f32_e32 v95, v95, v86
	v_add_f32_e32 v96, v96, v87
	v_bfe_u32 v86, v82, 2, 3
	v_mov_b32_e32 v88, v89
	v_cmp_eq_u32_e32 vcc, 1, v86
	v_cmp_eq_u32_e64 s[4:5], 2, v86
	s_nop 0
	v_cndmask_b32_e32 v88, v88, v90, vcc
	v_cndmask_b32_e64 v88, v88, v91, s[4:5]
	v_cmp_eq_u32_e32 vcc, 3, v86
	v_cmp_eq_u32_e64 s[4:5], 4, v86
	s_nop 0
	v_cndmask_b32_e32 v88, v88, v92, vcc
	v_cndmask_b32_e64 v88, v88, v93, s[4:5]
	v_cmp_eq_u32_e32 vcc, 5, v86
	v_cmp_eq_u32_e64 s[4:5], 6, v86
	s_nop 0
	v_cndmask_b32_e32 v88, v88, v94, vcc
	v_cndmask_b32_e64 v88, v88, v95, s[4:5]
	v_cmp_eq_u32_e32 vcc, 7, v86
	s_nop 0
	v_cndmask_b32_e32 v88, v88, v96, vcc
	v_fmamk_f32 v88, v88, 0x3c000000, v206
	v_cmp_gt_f32_e32 vcc, s36, v88
	v_mul_f32_e32 v178, 0x4f800000, v88
	s_nop 0
	v_cndmask_b32_e32 v88, v88, v178, vcc
	v_sqrt_f32_e32 v178, v88
	s_nop 0
	v_add_u32_e32 v179, -1, v178
	v_fma_f32 v180, -v179, v178, v88
	v_cmp_ge_f32_e64 s[4:5], 0, v180
	v_add_u32_e32 v180, 1, v178
	s_nop 0
	v_cndmask_b32_e64 v179, v178, v179, s[4:5]
	v_fma_f32 v178, -v180, v178, v88
	v_cmp_lt_f32_e64 s[4:5], 0, v178
	s_nop 1
	v_cndmask_b32_e64 v178, v179, v180, s[4:5]
	v_mul_f32_e32 v179, 0x37800000, v178
	v_cndmask_b32_e32 v178, v178, v179, vcc
	v_cmp_class_f32_e32 vcc, v88, v205
	s_nop 1
	v_cndmask_b32_e32 v88, v178, v88, vcc
	v_div_scale_f32 v178, s[4:5], v88, v88, s95
	v_rcp_f32_e32 v179, v178
	s_nop 0
	v_fma_f32 v180, -v178, v179, 1.0
	v_fmac_f32_e32 v179, v180, v179
	v_div_scale_f32 v180, vcc, s95, v88, s95
	v_mul_f32_e32 v181, v180, v179
	v_fma_f32 v182, -v178, v181, v180
	v_fmac_f32_e32 v181, v182, v179
	v_fma_f32 v178, -v178, v181, v180
	v_div_fmas_f32 v178, v178, v179, v181
	v_div_fixup_f32 v88, v178, v88, s95
	v_lshlrev_b32_e32 v84, 5, v211
	ds_bpermute_b32 v89, v84, v88
	ds_bpermute_b32 v90, v84, v88 offset:4
	ds_bpermute_b32 v91, v84, v88 offset:8
	ds_bpermute_b32 v92, v84, v88 offset:12
	ds_bpermute_b32 v93, v84, v88 offset:16
	ds_bpermute_b32 v94, v84, v88 offset:20
	ds_bpermute_b32 v95, v84, v88 offset:24
	ds_bpermute_b32 v96, v84, v88 offset:28
	s_waitcnt vmcnt(0) lgkmcnt(0)
; __device__ __forceinline__ int crow(int r, int hi) { return (r & 3) + 8 * (r >> 2) + 4 * hi; }
; __device__ __forceinline__ void attn_unit(LAS unsigned char* lds, bf16_t* Zg, const unsigned char* KVg, int S, int b, int h, int qb, const float* lq1, const float* lk1, const float* lq2, const float* lk2, const float* subln_g, const float* rel_bias, bool dostore = true) {
;     ...
;     if (mp == 1) {
; #pragma unroll
;         for (int db = 0; db < 4; ++db)
; #pragma unroll
;             for (int r = 0; r < 16; ++r) exch[(32 * qsub + crow(r, hi)) * 128 + db * 32 + r32] = o[db][r] * inv[r];
;     }
;     __syncthreads();
;     ...
;         for (int db = 0; db < 4; ++db) { const float sg = subln_g[db * 32 + r32];
; #pragma unroll
;             for (int r = 0; r < 16; ++r) exch[(32 * qsub + crow(r, hi)) * 128 + db * 32 + r32] = o[db][r] * ss[r] * sg; }
	v_mul_f32_e32 v58, v58, v89
	v_mul_f32_e32 v58, v58, v190
	v_mul_f32_e32 v42, v42, v89
	v_mul_f32_e32 v42, v42, v191
	ds_write2_b32 v108, v58, v42 offset1:32
	v_mul_f32_e32 v26, v26, v89
	v_mul_f32_e32 v26, v26, v192
	v_mul_f32_e32 v10, v10, v89
	v_mul_f32_e32 v10, v10, v193
	ds_write2_b32 v108, v26, v10 offset0:64 offset1:96
	v_mul_f32_e32 v59, v59, v90
	v_mul_f32_e32 v59, v59, v190
	v_mul_f32_e32 v43, v43, v90
	v_mul_f32_e32 v43, v43, v191
	ds_write2_b32 v108, v59, v43 offset0:128 offset1:160
	v_mul_f32_e32 v27, v27, v90
	v_mul_f32_e32 v27, v27, v192
	v_mul_f32_e32 v11, v11, v90
	v_mul_f32_e32 v11, v11, v193
	ds_write2_b32 v108, v27, v11 offset0:192 offset1:224
	v_mul_f32_e32 v60, v60, v91
	v_mul_f32_e32 v60, v60, v190
	v_mul_f32_e32 v44, v44, v91
	v_mul_f32_e32 v44, v44, v191
	ds_write2_b32 v109, v60, v44 offset1:32
	v_mul_f32_e32 v28, v28, v91
	v_mul_f32_e32 v28, v28, v192
	v_mul_f32_e32 v12, v12, v91
	v_mul_f32_e32 v12, v12, v193
	ds_write2_b32 v109, v28, v12 offset0:64 offset1:96
	v_mul_f32_e32 v61, v61, v92
	v_mul_f32_e32 v61, v61, v190
	v_mul_f32_e32 v45, v45, v92
	v_mul_f32_e32 v45, v45, v191
	ds_write2_b32 v109, v61, v45 offset0:128 offset1:160
	v_mul_f32_e32 v29, v29, v92
	v_mul_f32_e32 v29, v29, v192
	v_mul_f32_e32 v13, v13, v92
	v_mul_f32_e32 v13, v13, v193
	ds_write2_b32 v109, v29, v13 offset0:192 offset1:224
	v_mul_f32_e32 v62, v62, v93
	v_mul_f32_e32 v62, v62, v190
	v_mul_f32_e32 v46, v46, v93
	v_mul_f32_e32 v46, v46, v191
	ds_write2_b32 v110, v62, v46 offset1:32
	v_mul_f32_e32 v30, v30, v93
	v_mul_f32_e32 v30, v30, v192
	v_mul_f32_e32 v14, v14, v93
	v_mul_f32_e32 v14, v14, v193
	ds_write2_b32 v110, v30, v14 offset0:64 offset1:96
	v_mul_f32_e32 v63, v63, v94
	v_mul_f32_e32 v63, v63, v190
	v_mul_f32_e32 v47, v47, v94
	v_mul_f32_e32 v47, v47, v191
	ds_write2_b32 v110, v63, v47 offset0:128 offset1:160
	v_mul_f32_e32 v31, v31, v94
	v_mul_f32_e32 v31, v31, v192
	v_mul_f32_e32 v15, v15, v94
	v_mul_f32_e32 v15, v15, v193
	ds_write2_b32 v110, v31, v15 offset0:192 offset1:224
	v_mul_f32_e32 v64, v64, v95
	v_mul_f32_e32 v64, v64, v190
	v_mul_f32_e32 v48, v48, v95
	v_mul_f32_e32 v48, v48, v191
	ds_write2_b32 v111, v64, v48 offset1:32
	v_mul_f32_e32 v32, v32, v95
	v_mul_f32_e32 v32, v32, v192
	v_mul_f32_e32 v16, v16, v95
	v_mul_f32_e32 v16, v16, v193
	ds_write2_b32 v111, v32, v16 offset0:64 offset1:96
	v_mul_f32_e32 v65, v65, v96
	v_mul_f32_e32 v65, v65, v190
	v_mul_f32_e32 v49, v49, v96
	v_mul_f32_e32 v49, v49, v191
	ds_write2_b32 v111, v65, v49 offset0:128 offset1:160
	v_mul_f32_e32 v33, v33, v96
	v_mul_f32_e32 v33, v33, v192
	v_mul_f32_e32 v17, v17, v96
	v_mul_f32_e32 v17, v17, v193
	ds_write2_b32 v111, v33, v17 offset0:192 offset1:224
	s_branch .LBB0_187
.Lcmb_map0:
	v_or_b32_e32 v0, s84, v211
	v_lshlrev_b32_e32 v0, 9, v0
	v_add3_u32 v0, 0, v82, v0
	global_load_dword v190, v82, s[68:69]
	global_load_dword v191, v82, s[68:69] offset:128
	global_load_dword v192, v82, s[68:69] offset:256
	global_load_dword v193, v82, s[68:69] offset:384
	v_add_u32_e32 v105, 0x400, v0
	v_add_u32_e32 v106, 0x1000, v0
	v_add_u32_e32 v107, 0x1400, v0
	v_add_u32_e32 v108, 0x2000, v0
	v_add_u32_e32 v109, 0x2400, v0
	v_add_u32_e32 v110, 0x3000, v0
	v_add_u32_e32 v111, 0x3400, v0
	s_waitcnt lgkmcnt(0)
	v_mul_f32_e32 v89, v58, v70
	v_mul_f32_e32 v90, v42, v70
	ds_write2_b32 v108, v89, v90 offset1:32
	v_mul_f32_e32 v91, v26, v70
	v_mul_f32_e32 v92, v10, v70
	ds_write2_b32 v108, v91, v92 offset0:64 offset1:96
	v_mul_f32_e32 v93, v59, v71
	v_mul_f32_e32 v94, v43, v71
	ds_write2_b32 v108, v93, v94 offset0:128 offset1:160
	v_mul_f32_e32 v95, v27, v71
	v_mul_f32_e32 v96, v11, v71
	ds_write2_b32 v108, v95, v96 offset0:192 offset1:224
	v_mul_f32_e32 v97, v60, v72
	v_mul_f32_e32 v98, v44, v72
	ds_write2_b32 v109, v97, v98 offset1:32
	v_mul_f32_e32 v99, v28, v72
	v_mul_f32_e32 v100, v12, v72
	ds_write2_b32 v109, v99, v100 offset0:64 offset1:96
	v_mul_f32_e32 v101, v61, v73
	v_mul_f32_e32 v102, v45, v73
	ds_write2_b32 v109, v101, v102 offset0:128 offset1:160
	v_mul_f32_e32 v103, v29, v73
	v_mul_f32_e32 v104, v13, v73
	ds_write2_b32 v109, v103, v104 offset0:192 offset1:224
	v_mul_f32_e32 v89, v62, v66
	v_mul_f32_e32 v90, v46, v66
	ds_write2_b32 v110, v89, v90 offset1:32
	v_mul_f32_e32 v91, v30, v66
	v_mul_f32_e32 v92, v14, v66
	ds_write2_b32 v110, v91, v92 offset0:64 offset1:96
	v_mul_f32_e32 v93, v63, v67
	v_mul_f32_e32 v94, v47, v67
	ds_write2_b32 v110, v93, v94 offset0:128 offset1:160
	v_mul_f32_e32 v95, v31, v67
	v_mul_f32_e32 v96, v15, v67
	ds_write2_b32 v110, v95, v96 offset0:192 offset1:224
	v_mul_f32_e32 v97, v64, v68
	v_mul_f32_e32 v98, v48, v68
	ds_write2_b32 v111, v97, v98 offset1:32
	v_mul_f32_e32 v99, v32, v68
	v_mul_f32_e32 v100, v16, v68
	ds_write2_b32 v111, v99, v100 offset0:64 offset1:96
	v_mul_f32_e32 v101, v65, v69
	v_mul_f32_e32 v102, v49, v69
	ds_write2_b32 v111, v101, v102 offset0:128 offset1:160
	v_mul_f32_e32 v103, v33, v69
	v_mul_f32_e32 v104, v17, v69
	ds_write2_b32 v111, v103, v104 offset0:192 offset1:224
	s_waitcnt lgkmcnt(0)
	s_barrier
; __device__ __forceinline__ int crow(int r, int hi) { return (r & 3) + 8 * (r >> 2) + 4 * hi; }
; __device__ __forceinline__ void attn_unit(LAS unsigned char* lds, bf16_t* Zg, const unsigned char* KVg, int S, int b, int h, int qb, const float* lq1, const float* lk1, const float* lq2, const float* lk2, const float* subln_g, const float* rel_bias, bool dostore = true) {
;     ...
;     if (mp == 0) {
;         float ss[16];
; #pragma unroll
;         for (int r = 0; r < 16; ++r) { float a = 0.f;
; #pragma unroll
;             for (int db = 0; db < 4; ++db) { const float d = o[db][r] * inv[r] - exch[(32 * qsub + crow(r, hi)) * 128 + db * 32 + r32]; o[db][r] = d; a += d * d; }
;             ss[r] = a; }
	ds_read2_b32 v[178:179], v0 offset1:32
	ds_read2_b32 v[180:181], v0 offset0:64 offset1:96
	ds_read2_b32 v[182:183], v0 offset0:128 offset1:160
	ds_read2_b32 v[184:185], v0 offset0:192 offset1:224
	ds_read2_b32 v[186:187], v105 offset1:32
	ds_read2_b32 v[188:189], v105 offset0:64 offset1:96
	s_waitcnt lgkmcnt(5)
	v_fma_f32 v50, v50, v78, -v178
	v_fma_f32 v34, v34, v78, -v179
	ds_read2_b32 v[178:179], v105 offset0:128 offset1:160
	s_waitcnt lgkmcnt(5)
	v_fma_f32 v18, v18, v78, -v180
	v_fma_f32 v2, v2, v78, -v181
	ds_read2_b32 v[180:181], v105 offset0:192 offset1:224
	v_mul_f32_e32 v89, v34, v34
	v_fmac_f32_e32 v89, v50, v50
	v_fmac_f32_e32 v89, v18, v18
	v_fmac_f32_e32 v89, v2, v2
	s_waitcnt lgkmcnt(5)
	v_fma_f32 v51, v51, v79, -v182
	v_fma_f32 v35, v35, v79, -v183
	ds_read2_b32 v[182:183], v106 offset1:32
	s_waitcnt lgkmcnt(5)
	v_fma_f32 v19, v19, v79, -v184
	v_fma_f32 v3, v3, v79, -v185
	ds_read2_b32 v[184:185], v106 offset0:64 offset1:96
	v_mul_f32_e32 v90, v35, v35
	v_fmac_f32_e32 v90, v51, v51
	v_fmac_f32_e32 v90, v19, v19
	v_fmac_f32_e32 v90, v3, v3
	s_waitcnt lgkmcnt(5)
	v_fma_f32 v52, v52, v80, -v186
	v_fma_f32 v36, v36, v80, -v187
	ds_read2_b32 v[186:187], v106 offset0:128 offset1:160
	s_waitcnt lgkmcnt(5)
	v_fma_f32 v20, v20, v80, -v188
	v_fma_f32 v4, v4, v80, -v189
	ds_read2_b32 v[188:189], v106 offset0:192 offset1:224
	v_mul_f32_e32 v91, v36, v36
	v_fmac_f32_e32 v91, v52, v52
	v_fmac_f32_e32 v91, v20, v20
	v_fmac_f32_e32 v91, v4, v4
	s_waitcnt lgkmcnt(5)
	v_fma_f32 v53, v53, v81, -v178
	v_fma_f32 v37, v37, v81, -v179
	ds_read2_b32 v[178:179], v107 offset1:32
	s_waitcnt lgkmcnt(5)
	v_fma_f32 v21, v21, v81, -v180
	v_fma_f32 v5, v5, v81, -v181
	ds_read2_b32 v[180:181], v107 offset0:64 offset1:96
	v_mul_f32_e32 v92, v37, v37
	v_fmac_f32_e32 v92, v53, v53
	v_fmac_f32_e32 v92, v21, v21
	v_fmac_f32_e32 v92, v5, v5
	s_waitcnt lgkmcnt(5)
	v_fma_f32 v54, v54, v74, -v182
	v_fma_f32 v38, v38, v74, -v183
	ds_read2_b32 v[182:183], v107 offset0:128 offset1:160
	s_waitcnt lgkmcnt(5)
	v_fma_f32 v22, v22, v74, -v184
	v_fma_f32 v6, v6, v74, -v185
	ds_read2_b32 v[184:185], v107 offset0:192 offset1:224
	v_mul_f32_e32 v93, v38, v38
	v_fmac_f32_e32 v93, v54, v54
	v_fmac_f32_e32 v93, v22, v22
	v_fmac_f32_e32 v93, v6, v6
	s_waitcnt lgkmcnt(5)
	v_fma_f32 v55, v55, v75, -v186
	v_fma_f32 v39, v39, v75, -v187
	s_waitcnt lgkmcnt(4)
	v_fma_f32 v23, v23, v75, -v188
	v_fma_f32 v7, v7, v75, -v189
	v_mul_f32_e32 v94, v39, v39
	v_fmac_f32_e32 v94, v55, v55
	v_fmac_f32_e32 v94, v23, v23
	v_fmac_f32_e32 v94, v7, v7
	s_waitcnt lgkmcnt(3)
	v_fma_f32 v56, v56, v76, -v178
	v_fma_f32 v40, v40, v76, -v179
	s_waitcnt lgkmcnt(2)
	v_fma_f32 v24, v24, v76, -v180
	v_fma_f32 v8, v8, v76, -v181
	v_mul_f32_e32 v95, v40, v40
	v_fmac_f32_e32 v95, v56, v56
	v_fmac_f32_e32 v95, v24, v24
	v_fmac_f32_e32 v95, v8, v8
	s_waitcnt lgkmcnt(1)
	v_fma_f32 v57, v57, v77, -v182
	v_fma_f32 v41, v41, v77, -v183
	s_waitcnt lgkmcnt(0)
	v_fma_f32 v25, v25, v77, -v184
	v_fma_f32 v9, v9, v77, -v185
	v_mul_f32_e32 v96, v41, v41
	v_fmac_f32_e32 v96, v57, v57
	v_fmac_f32_e32 v96, v25, v25
	v_fmac_f32_e32 v96, v9, v9
	s_nop 1
	v_mov_b32_dpp v84, v89 quad_perm:[1,0,3,2] row_mask:0xf bank_mask:0xf
	v_mov_b32_dpp v85, v90 quad_perm:[1,0,3,2] row_mask:0xf bank_mask:0xf
	v_mov_b32_dpp v86, v91 quad_perm:[1,0,3,2] row_mask:0xf bank_mask:0xf
	v_mov_b32_dpp v87, v92 quad_perm:[1,0,3,2] row_mask:0xf bank_mask:0xf
	v_add_f32_e32 v89, v89, v84
	v_add_f32_e32 v90, v90, v85
	v_add_f32_e32 v91, v91, v86
	v_add_f32_e32 v92, v92, v87
	v_mov_b32_dpp v84, v89 quad_perm:[2,3,0,1] row_mask:0xf bank_mask:0xf
	v_mov_b32_dpp v85, v90 quad_perm:[2,3,0,1] row_mask:0xf bank_mask:0xf
	v_mov_b32_dpp v86, v91 quad_perm:[2,3,0,1] row_mask:0xf bank_mask:0xf
	v_mov_b32_dpp v87, v92 quad_perm:[2,3,0,1] row_mask:0xf bank_mask:0xf
	v_add_f32_e32 v89, v89, v84
	v_add_f32_e32 v90, v90, v85
	v_add_f32_e32 v91, v91, v86
	v_add_f32_e32 v92, v92, v87
	v_mov_b32_dpp v84, v89 row_half_mirror row_mask:0xf bank_mask:0xf
	v_mov_b32_dpp v85, v90 row_half_mirror row_mask:0xf bank_mask:0xf
	v_mov_b32_dpp v86, v91 row_half_mirror row_mask:0xf bank_mask:0xf
	v_mov_b32_dpp v87, v92 row_half_mirror row_mask:0xf bank_mask:0xf
	v_add_f32_e32 v89, v89, v84
	v_add_f32_e32 v90, v90, v85
	v_add_f32_e32 v91, v91, v86
	v_add_f32_e32 v92, v92, v87
	v_mov_b32_dpp v84, v89 row_ror:8 row_mask:0xf bank_mask:0xf
	v_mov_b32_dpp v85, v90 row_ror:8 row_mask:0xf bank_mask:0xf
	v_mov_b32_dpp v86, v91 row_ror:8 row_mask:0xf bank_mask:0xf
	v_mov_b32_dpp v87, v92 row_ror:8 row_mask:0xf bank_mask:0xf
	v_add_f32_e32 v89, v89, v84
	v_add_f32_e32 v90, v90, v85
	v_add_f32_e32 v91, v91, v86
	v_add_f32_e32 v92, v92, v87
	v_mov_b32_e32 v84, v89
	v_mov_b32_e32 v85, v90
	v_mov_b32_e32 v86, v91
	v_mov_b32_e32 v87, v92
	v_permlane16_swap_b32_e32 v84, v89
	v_permlane16_swap_b32_e32 v85, v90
	v_permlane16_swap_b32_e32 v86, v91
	v_permlane16_swap_b32_e32 v87, v92
	v_add_f32_e32 v89, v89, v84
	v_add_f32_e32 v90, v90, v85
	v_add_f32_e32 v91, v91, v86
	v_add_f32_e32 v92, v92, v87
	s_nop 1
	v_mov_b32_dpp v84, v93 quad_perm:[1,0,3,2] row_mask:0xf bank_mask:0xf
	v_mov_b32_dpp v85, v94 quad_perm:[1,0,3,2] row_mask:0xf bank_mask:0xf
	v_mov_b32_dpp v86, v95 quad_perm:[1,0,3,2] row_mask:0xf bank_mask:0xf
	v_mov_b32_dpp v87, v96 quad_perm:[1,0,3,2] row_mask:0xf bank_mask:0xf
	v_add_f32_e32 v93, v93, v84
	v_add_f32_e32 v94, v94, v85
	v_add_f32_e32 v95, v95, v86
	v_add_f32_e32 v96, v96, v87
	v_mov_b32_dpp v84, v93 quad_perm:[2,3,0,1] row_mask:0xf bank_mask:0xf
	v_mov_b32_dpp v85, v94 quad_perm:[2,3,0,1] row_mask:0xf bank_mask:0xf
	v_mov_b32_dpp v86, v95 quad_perm:[2,3,0,1] row_mask:0xf bank_mask:0xf
; __device__ __forceinline__ float shx(float v, int o, int lane) { return __int_as_float(__builtin_amdgcn_ds_bpermute((lane ^ o) << 2, __float_as_int(v))); }
; __device__ __forceinline__ int crow(int r, int hi) { return (r & 3) + 8 * (r >> 2) + 4 * hi; }
; __device__ __forceinline__ void attn_unit(LAS unsigned char* lds, bf16_t* Zg, const unsigned char* KVg, int S, int b, int h, int qb, const float* lq1, const float* lk1, const float* lq2, const float* lk2, const float* subln_g, const float* rel_bias, bool dostore = true) {
;     ...
;         for (int r = 0; r < 16; ++r) {
; #pragma unroll
;             for (int sft = 1; sft < 32; sft <<= 1) ss[r] += shx(ss[r], sft, lane);
;             ss[r] = (1.0f - LAMBDA_INIT) / sqrtf(ss[r] * (1.0f / 128.0f) + EPS); }
; #pragma unroll
;         for (int db = 0; db < 4; ++db) { const float sg = subln_g[db * 32 + r32];
; #pragma unroll
;             for (int r = 0; r < 16; ++r) exch[(32 * qsub + crow(r, hi)) * 128 + db * 32 + r32] = o[db][r] * ss[r] * sg; }
	v_mov_b32_dpp v87, v96 quad_perm:[2,3,0,1] row_mask:0xf bank_mask:0xf
	v_add_f32_e32 v93, v93, v84
	v_add_f32_e32 v94, v94, v85
	v_add_f32_e32 v95, v95, v86
	v_add_f32_e32 v96, v96, v87
	v_mov_b32_dpp v84, v93 row_half_mirror row_mask:0xf bank_mask:0xf
	v_mov_b32_dpp v85, v94 row_half_mirror row_mask:0xf bank_mask:0xf
	v_mov_b32_dpp v86, v95 row_half_mirror row_mask:0xf bank_mask:0xf
	v_mov_b32_dpp v87, v96 row_half_mirror row_mask:0xf bank_mask:0xf
	v_add_f32_e32 v93, v93, v84
	v_add_f32_e32 v94, v94, v85
	v_add_f32_e32 v95, v95, v86
	v_add_f32_e32 v96, v96, v87
	v_mov_b32_dpp v84, v93 row_ror:8 row_mask:0xf bank_mask:0xf
	v_mov_b32_dpp v85, v94 row_ror:8 row_mask:0xf bank_mask:0xf
	v_mov_b32_dpp v86, v95 row_ror:8 row_mask:0xf bank_mask:0xf
	v_mov_b32_dpp v87, v96 row_ror:8 row_mask:0xf bank_mask:0xf
	v_add_f32_e32 v93, v93, v84
	v_add_f32_e32 v94, v94, v85
	v_add_f32_e32 v95, v95, v86
	v_add_f32_e32 v96, v96, v87
	v_mov_b32_e32 v84, v93
	v_mov_b32_e32 v85, v94
	v_mov_b32_e32 v86, v95
	v_mov_b32_e32 v87, v96
	v_permlane16_swap_b32_e32 v84, v93
	v_permlane16_swap_b32_e32 v85, v94
	v_permlane16_swap_b32_e32 v86, v95
	v_permlane16_swap_b32_e32 v87, v96
	v_add_f32_e32 v93, v93, v84
	v_add_f32_e32 v94, v94, v85
	v_add_f32_e32 v95, v95, v86
	v_add_f32_e32 v96, v96, v87
	v_bfe_u32 v86, v82, 2, 3
	v_mov_b32_e32 v88, v89
	v_cmp_eq_u32_e32 vcc, 1, v86
	v_cmp_eq_u32_e64 s[4:5], 2, v86
	s_nop 0
	v_cndmask_b32_e32 v88, v88, v90, vcc
	v_cndmask_b32_e64 v88, v88, v91, s[4:5]
	v_cmp_eq_u32_e32 vcc, 3, v86
	v_cmp_eq_u32_e64 s[4:5], 4, v86
	s_nop 0
	v_cndmask_b32_e32 v88, v88, v92, vcc
	v_cndmask_b32_e64 v88, v88, v93, s[4:5]
	v_cmp_eq_u32_e32 vcc, 5, v86
	v_cmp_eq_u32_e64 s[4:5], 6, v86
	s_nop 0
	v_cndmask_b32_e32 v88, v88, v94, vcc
	v_cndmask_b32_e64 v88, v88, v95, s[4:5]
	v_cmp_eq_u32_e32 vcc, 7, v86
	s_nop 0
	v_cndmask_b32_e32 v88, v88, v96, vcc
	v_fmamk_f32 v88, v88, 0x3c000000, v206
	v_cmp_gt_f32_e32 vcc, s36, v88
	v_mul_f32_e32 v178, 0x4f800000, v88
	s_nop 0
	v_cndmask_b32_e32 v88, v88, v178, vcc
	v_sqrt_f32_e32 v178, v88
	s_nop 0
	v_add_u32_e32 v179, -1, v178
	v_fma_f32 v180, -v179, v178, v88
	v_cmp_ge_f32_e64 s[4:5], 0, v180
	v_add_u32_e32 v180, 1, v178
	s_nop 0
	v_cndmask_b32_e64 v179, v178, v179, s[4:5]
	v_fma_f32 v178, -v180, v178, v88
	v_cmp_lt_f32_e64 s[4:5], 0, v178
	s_nop 1
	v_cndmask_b32_e64 v178, v179, v180, s[4:5]
	v_mul_f32_e32 v179, 0x37800000, v178
	v_cndmask_b32_e32 v178, v178, v179, vcc
	v_cmp_class_f32_e32 vcc, v88, v205
	s_nop 1
	v_cndmask_b32_e32 v88, v178, v88, vcc
	v_div_scale_f32 v178, s[4:5], v88, v88, s95
	v_rcp_f32_e32 v179, v178
	s_nop 0
	v_fma_f32 v180, -v178, v179, 1.0
	v_fmac_f32_e32 v179, v180, v179
	v_div_scale_f32 v180, vcc, s95, v88, s95
	v_mul_f32_e32 v181, v180, v179
	v_fma_f32 v182, -v178, v181, v180
	v_fmac_f32_e32 v181, v182, v179
	v_fma_f32 v178, -v178, v181, v180
	v_div_fmas_f32 v178, v178, v179, v181
	v_div_fixup_f32 v88, v178, v88, s95
	v_lshlrev_b32_e32 v84, 5, v211
	ds_bpermute_b32 v89, v84, v88
	ds_bpermute_b32 v90, v84, v88 offset:4
	ds_bpermute_b32 v91, v84, v88 offset:8
	ds_bpermute_b32 v92, v84, v88 offset:12
	ds_bpermute_b32 v93, v84, v88 offset:16
	ds_bpermute_b32 v94, v84, v88 offset:20
	ds_bpermute_b32 v95, v84, v88 offset:24
	ds_bpermute_b32 v96, v84, v88 offset:28
	s_waitcnt vmcnt(0) lgkmcnt(0)
	v_mul_f32_e32 v50, v50, v89
	v_mul_f32_e32 v50, v50, v190
	v_mul_f32_e32 v34, v34, v89
	v_mul_f32_e32 v34, v34, v191
	ds_write2_b32 v0, v50, v34 offset1:32
	v_mul_f32_e32 v18, v18, v89
	v_mul_f32_e32 v18, v18, v192
	v_mul_f32_e32 v2, v2, v89
	v_mul_f32_e32 v2, v2, v193
	ds_write2_b32 v0, v18, v2 offset0:64 offset1:96
	v_mul_f32_e32 v51, v51, v90
	v_mul_f32_e32 v51, v51, v190
	v_mul_f32_e32 v35, v35, v90
	v_mul_f32_e32 v35, v35, v191
	ds_write2_b32 v0, v51, v35 offset0:128 offset1:160
	v_mul_f32_e32 v19, v19, v90
	v_mul_f32_e32 v19, v19, v192
	v_mul_f32_e32 v3, v3, v90
	v_mul_f32_e32 v3, v3, v193
	ds_write2_b32 v0, v19, v3 offset0:192 offset1:224
	v_mul_f32_e32 v52, v52, v91
	v_mul_f32_e32 v52, v52, v190
	v_mul_f32_e32 v36, v36, v91
	v_mul_f32_e32 v36, v36, v191
	ds_write2_b32 v105, v52, v36 offset1:32
	v_mul_f32_e32 v20, v20, v91
	v_mul_f32_e32 v20, v20, v192
	v_mul_f32_e32 v4, v4, v91
	v_mul_f32_e32 v4, v4, v193
	ds_write2_b32 v105, v20, v4 offset0:64 offset1:96
	v_mul_f32_e32 v53, v53, v92
	v_mul_f32_e32 v53, v53, v190
	v_mul_f32_e32 v37, v37, v92
	v_mul_f32_e32 v37, v37, v191
	ds_write2_b32 v105, v53, v37 offset0:128 offset1:160
	v_mul_f32_e32 v21, v21, v92
	v_mul_f32_e32 v21, v21, v192
	v_mul_f32_e32 v5, v5, v92
	v_mul_f32_e32 v5, v5, v193
	ds_write2_b32 v105, v21, v5 offset0:192 offset1:224
	v_mul_f32_e32 v54, v54, v93
	v_mul_f32_e32 v54, v54, v190
	v_mul_f32_e32 v38, v38, v93
	v_mul_f32_e32 v38, v38, v191
	ds_write2_b32 v106, v54, v38 offset1:32
	v_mul_f32_e32 v22, v22, v93
	v_mul_f32_e32 v22, v22, v192
	v_mul_f32_e32 v6, v6, v93
	v_mul_f32_e32 v6, v6, v193
	ds_write2_b32 v106, v22, v6 offset0:64 offset1:96
	v_mul_f32_e32 v55, v55, v94
	v_mul_f32_e32 v55, v55, v190
	v_mul_f32_e32 v39, v39, v94
	v_mul_f32_e32 v39, v39, v191
	ds_write2_b32 v106, v55, v39 offset0:128 offset1:160
	v_mul_f32_e32 v23, v23, v94
	v_mul_f32_e32 v23, v23, v192
	v_mul_f32_e32 v7, v7, v94
	v_mul_f32_e32 v7, v7, v193
	ds_write2_b32 v106, v23, v7 offset0:192 offset1:224
	v_mul_f32_e32 v56, v56, v95
	v_mul_f32_e32 v56, v56, v190
	v_mul_f32_e32 v40, v40, v95
	v_mul_f32_e32 v40, v40, v191
	ds_write2_b32 v107, v56, v40 offset1:32
	v_mul_f32_e32 v24, v24, v95
	v_mul_f32_e32 v24, v24, v192
	v_mul_f32_e32 v8, v8, v95
	v_mul_f32_e32 v8, v8, v193
	ds_write2_b32 v107, v24, v8 offset0:64 offset1:96
	v_mul_f32_e32 v57, v57, v96
	v_mul_f32_e32 v57, v57, v190
	v_mul_f32_e32 v41, v41, v96
	v_mul_f32_e32 v41, v41, v191
	ds_write2_b32 v107, v57, v41 offset0:128 offset1:160
	v_mul_f32_e32 v25, v25, v96
	v_mul_f32_e32 v25, v25, v192
	v_mul_f32_e32 v9, v9, v96
	v_mul_f32_e32 v9, v9, v193
	ds_write2_b32 v107, v25, v9 offset0:192 offset1:224
	s_branch .LBB0_187
